# v19 + RG-LRU post-wait path: loop-top barrier only for the first task, carry fold over 8 granule pairs per LDS round trip
# speedup vs baseline: 1.0056x; 1.0056x over previous
.LBB0_357:
	s_or_b64 exec, exec, s[0:1]
	s_cmp_lt_i32 s33, 1
	v_mov_b32_e32 v102, 0
	s_waitcnt lgkmcnt(0)
	s_barrier
	s_cbranch_scc1 .LBB0_306
	v_mov_b32_e32 v103, v146
	s_cmp_lt_i32 s33, 8
	s_cbranch_scc1 .Lrnn_lb4_chk
.Lrnn_lb8:
	ds_read_b64 v[226:227], v103
	ds_read_b64 v[228:229], v103 offset:512
	ds_read_b64 v[230:231], v103 offset:1024
	ds_read_b64 v[232:233], v103 offset:1536
	ds_read_b64 v[240:241], v103 offset:2048
	ds_read_b64 v[242:243], v103 offset:2560
	ds_read_b64 v[244:245], v103 offset:3072
	ds_read_b64 v[246:247], v103 offset:3584
	s_add_i32 s33, s33, -8
	v_add_u32_e32 v103, 0x1000, v103
	s_waitcnt lgkmcnt(7)
	v_fma_f32 v102, v102, v226, v227
	s_waitcnt lgkmcnt(6)
	v_fma_f32 v102, v102, v228, v229
	s_waitcnt lgkmcnt(5)
	v_fma_f32 v102, v102, v230, v231
	s_waitcnt lgkmcnt(4)
	v_fma_f32 v102, v102, v232, v233
	s_waitcnt lgkmcnt(3)
	v_fma_f32 v102, v102, v240, v241
	s_waitcnt lgkmcnt(2)
	v_fma_f32 v102, v102, v242, v243
	s_waitcnt lgkmcnt(1)
	v_fma_f32 v102, v102, v244, v245
	s_waitcnt lgkmcnt(0)
	v_fma_f32 v102, v102, v246, v247
	s_cmp_lt_i32 s33, 8
	s_cbranch_scc0 .Lrnn_lb8
.Lrnn_lb4_chk:
	s_cmp_lt_i32 s33, 4
	s_cbranch_scc1 .Lrnn_lb_tail
